# epilogue-scoped priority raise (s_setprio 2) for the leading wave half in P1 and P5 epilogues, reset at unit advance
# speedup vs baseline: 1.0018x; 1.0018x over previous
.LBB0_380:
	s_setprio 0
	s_andn2_b64 vcc, exec, s[4:5]
	s_mov_b32 s96, s28
	s_mov_b32 s80, s66
	s_mov_b64 s[82:83], s[62:63]
	s_mov_b64 s[4:5], s[26:27]
	s_cbranch_vccz .LBB0_490

.LBB0_384:
	ds_read_b128 v[134:137], v199
	ds_read_b128 v[138:141], v200
	ds_read_b128 v[142:145], v201
	ds_read_b128 v[146:149], v202
	ds_read_b128 v[150:153], v203
	ds_read_b128 v[174:177], v204
	ds_read_b128 v[178:181], v205
	ds_read_b128 v[182:185], v206
	s_add_u32 s24, s4, vcc_lo
	s_addc_u32 s25, s5, vcc_hi
	s_add_u32 s24, s24, 0x100
	s_addc_u32 s25, s25, 0
	s_add_u32 s82, s39, vcc_lo
	s_addc_u32 s83, s67, vcc_hi
	s_cmpk_eq_i32 vcc_lo, 0x700
	s_cselect_b32 s87, s29, s83
	s_cselect_b32 s86, s38, s82
	s_cselect_b32 s83, s34, s25
	s_cselect_b32 s82, s35, s24
	v_lshl_add_u64 v[154:155], v[132:133], 0, vcc
	v_lshl_add_u64 v[250:251], v[154:155], 0, s[48:49]
	s_add_i32 m0, s79, 0x8000
	s_mov_b64 s[24:25], 0x20080
	ds_read_b128 v[218:221], v207
	ds_read_b128 v[222:225], v207 offset:2048
	ds_read_b128 v[226:229], v208
	ds_read_b128 v[230:233], v208 offset:2048
	ds_read_b128 v[234:237], v207 offset:4096
	ds_read_b128 v[238:241], v207 offset:6144
	ds_read_b128 v[242:245], v208 offset:4096
	ds_read_b128 v[246:249], v208 offset:6144
	global_load_lds_dwordx4 v[250:251], off
	v_lshl_add_u64 v[250:251], v[154:155], 0, s[24:25]
	s_add_i32 m0, s79, 0xa000
	s_mov_b64 s[24:25], 0x60080
	global_load_lds_dwordx4 v[250:251], off
	v_lshl_add_u64 v[250:251], v[154:155], 0, s[50:51]
	s_add_i32 m0, s79, 0xc000
	v_lshl_add_u64 v[154:155], v[154:155], 0, s[24:25]
	global_load_lds_dwordx4 v[250:251], off
	s_add_i32 m0, s79, 0xe000
	s_nop 0
	global_load_lds_dwordx4 v[154:155], off
	s_waitcnt vmcnt(8)
	s_waitcnt lgkmcnt(0)
	s_barrier
	v_mfma_f32_16x16x32_bf16 v[128:131], v[134:137], v[218:221], v[128:131]
	v_mfma_f32_16x16x32_bf16 v[128:131], v[138:141], v[226:229], v[128:131]
	v_mfma_f32_16x16x32_bf16 v[112:115], v[138:141], v[230:233], v[112:115]
	v_mfma_f32_16x16x32_bf16 v[112:115], v[134:137], v[222:225], v[112:115]
	v_mfma_f32_16x16x32_bf16 v[96:99], v[134:137], v[234:237], v[96:99]
	v_mfma_f32_16x16x32_bf16 v[96:99], v[138:141], v[242:245], v[96:99]
	v_mfma_f32_16x16x32_bf16 v[80:83], v[138:141], v[246:249], v[80:83]
	v_mfma_f32_16x16x32_bf16 v[80:83], v[134:137], v[238:241], v[80:83]
	v_mfma_f32_16x16x32_bf16 v[76:79], v[142:145], v[238:241], v[76:79]
	v_mfma_f32_16x16x32_bf16 v[76:79], v[146:149], v[246:249], v[76:79]
	v_mfma_f32_16x16x32_bf16 v[92:95], v[146:149], v[242:245], v[92:95]
	v_mfma_f32_16x16x32_bf16 v[92:95], v[142:145], v[234:237], v[92:95]
	v_mfma_f32_16x16x32_bf16 v[108:111], v[142:145], v[222:225], v[108:111]
	v_mfma_f32_16x16x32_bf16 v[108:111], v[146:149], v[230:233], v[108:111]
	v_mfma_f32_16x16x32_bf16 v[124:127], v[146:149], v[226:229], v[124:127]
	v_mfma_f32_16x16x32_bf16 v[124:127], v[142:145], v[218:221], v[124:127]
	v_mfma_f32_16x16x32_bf16 v[120:123], v[150:153], v[218:221], v[120:123]
	v_mfma_f32_16x16x32_bf16 v[120:123], v[174:177], v[226:229], v[120:123]
	v_mfma_f32_16x16x32_bf16 v[104:107], v[174:177], v[230:233], v[104:107]
	v_mfma_f32_16x16x32_bf16 v[104:107], v[150:153], v[222:225], v[104:107]
	v_mfma_f32_16x16x32_bf16 v[88:91], v[150:153], v[234:237], v[88:91]
	v_mfma_f32_16x16x32_bf16 v[88:91], v[174:177], v[242:245], v[88:91]
	v_mfma_f32_16x16x32_bf16 v[72:75], v[174:177], v[246:249], v[72:75]
	v_mfma_f32_16x16x32_bf16 v[72:75], v[150:153], v[238:241], v[72:75]
	v_mfma_f32_16x16x32_bf16 v[68:71], v[178:181], v[238:241], v[68:71]
	v_mfma_f32_16x16x32_bf16 v[68:71], v[182:185], v[246:249], v[68:71]
	v_mfma_f32_16x16x32_bf16 v[84:87], v[182:185], v[242:245], v[84:87]
	v_mfma_f32_16x16x32_bf16 v[84:87], v[178:181], v[234:237], v[84:87]
	v_mfma_f32_16x16x32_bf16 v[100:103], v[178:181], v[222:225], v[100:103]
	v_mfma_f32_16x16x32_bf16 v[100:103], v[182:185], v[230:233], v[100:103]
	v_mfma_f32_16x16x32_bf16 v[116:119], v[182:185], v[226:229], v[116:119]
	v_mfma_f32_16x16x32_bf16 v[116:119], v[178:181], v[218:221], v[116:119]
	s_barrier
	s_add_i32 s24, s1, s77
	v_lshl_add_u64 v[154:155], s[86:87], 0, v[158:159]
	s_mov_b32 m0, s24
	ds_read_b128 v[218:221], v207 offset:16384
	ds_read_b128 v[222:225], v207 offset:18432
	ds_read_b128 v[226:229], v208 offset:16384
	ds_read_b128 v[230:233], v208 offset:18432
	ds_read_b128 v[234:237], v207 offset:20480
	ds_read_b128 v[238:241], v207 offset:22528
	ds_read_b128 v[242:245], v208 offset:20480
	ds_read_b128 v[246:249], v208 offset:22528
	global_load_lds_dwordx4 v[154:155], off
	v_lshl_add_u64 v[250:251], v[154:155], 0, s[14:15]
	s_add_i32 m0, s24, 0x2000
	s_add_i32 s24, s12, s77
	global_load_lds_dwordx4 v[250:251], off
	v_lshl_add_u64 v[250:251], v[154:155], 0, s[16:17]
	s_mov_b32 m0, s24
	s_nop 0
	global_load_lds_dwordx4 v[250:251], off
	v_lshl_add_u64 v[250:251], v[154:155], 0, s[18:19]
	s_add_i32 m0, s24, 0x2000
	s_nop 0
	global_load_lds_dwordx4 v[250:251], off
	s_waitcnt vmcnt(4)
	s_waitcnt lgkmcnt(0)
	s_barrier
	v_mfma_f32_16x16x32_bf16 v[64:67], v[134:137], v[218:221], v[64:67]
	v_mfma_f32_16x16x32_bf16 v[64:67], v[138:141], v[226:229], v[64:67]
	v_mfma_f32_16x16x32_bf16 v[48:51], v[138:141], v[230:233], v[48:51]
	v_mfma_f32_16x16x32_bf16 v[48:51], v[134:137], v[222:225], v[48:51]
	v_mfma_f32_16x16x32_bf16 v[32:35], v[134:137], v[234:237], v[32:35]
	v_mfma_f32_16x16x32_bf16 v[32:35], v[138:141], v[242:245], v[32:35]
	v_mfma_f32_16x16x32_bf16 v[16:19], v[138:141], v[246:249], v[16:19]
	v_mfma_f32_16x16x32_bf16 v[16:19], v[134:137], v[238:241], v[16:19]
	v_mfma_f32_16x16x32_bf16 v[12:15], v[142:145], v[238:241], v[12:15]
	v_mfma_f32_16x16x32_bf16 v[12:15], v[146:149], v[246:249], v[12:15]
	v_mfma_f32_16x16x32_bf16 v[28:31], v[146:149], v[242:245], v[28:31]
	v_mfma_f32_16x16x32_bf16 v[28:31], v[142:145], v[234:237], v[28:31]
	v_mfma_f32_16x16x32_bf16 v[44:47], v[142:145], v[222:225], v[44:47]
	v_mfma_f32_16x16x32_bf16 v[44:47], v[146:149], v[230:233], v[44:47]
	v_mfma_f32_16x16x32_bf16 v[60:63], v[146:149], v[226:229], v[60:63]
	v_mfma_f32_16x16x32_bf16 v[60:63], v[142:145], v[218:221], v[60:63]
	v_mfma_f32_16x16x32_bf16 v[56:59], v[150:153], v[218:221], v[56:59]
	v_mfma_f32_16x16x32_bf16 v[56:59], v[174:177], v[226:229], v[56:59]
	v_mfma_f32_16x16x32_bf16 v[40:43], v[174:177], v[230:233], v[40:43]
	v_mfma_f32_16x16x32_bf16 v[40:43], v[150:153], v[222:225], v[40:43]
	v_mfma_f32_16x16x32_bf16 v[24:27], v[150:153], v[234:237], v[24:27]
	v_mfma_f32_16x16x32_bf16 v[24:27], v[174:177], v[242:245], v[24:27]
	v_mfma_f32_16x16x32_bf16 v[8:11], v[174:177], v[246:249], v[8:11]
	v_mfma_f32_16x16x32_bf16 v[8:11], v[150:153], v[238:241], v[8:11]
	v_mfma_f32_16x16x32_bf16 v[4:7], v[178:181], v[238:241], v[4:7]
	v_mfma_f32_16x16x32_bf16 v[4:7], v[182:185], v[246:249], v[4:7]
	v_mfma_f32_16x16x32_bf16 v[20:23], v[182:185], v[242:245], v[20:23]
	v_mfma_f32_16x16x32_bf16 v[20:23], v[178:181], v[234:237], v[20:23]
	v_mfma_f32_16x16x32_bf16 v[36:39], v[178:181], v[222:225], v[36:39]
	v_mfma_f32_16x16x32_bf16 v[36:39], v[182:185], v[230:233], v[36:39]
	v_mfma_f32_16x16x32_bf16 v[52:55], v[182:185], v[226:229], v[52:55]
	v_mfma_f32_16x16x32_bf16 v[52:55], v[178:181], v[218:221], v[52:55]
	s_barrier
	ds_read_b128 v[134:137], v213
	ds_read_b128 v[138:141], v214
	ds_read_b128 v[142:145], v209
	ds_read_b128 v[146:149], v210
	ds_read_b128 v[150:153], v215
	ds_read_b128 v[174:177], v216
	ds_read_b128 v[178:181], v211
	ds_read_b128 v[182:185], v212
	s_mov_b32 m0, s79
	v_lshl_add_u64 v[250:251], s[82:83], 0, v[0:1]
	ds_read_b128 v[218:221], v207 offset:32768
	ds_read_b128 v[222:225], v207 offset:34816
	ds_read_b128 v[226:229], v208 offset:32768
	ds_read_b128 v[230:233], v208 offset:34816
	ds_read_b128 v[234:237], v207 offset:36864
	ds_read_b128 v[238:241], v207 offset:38912
	ds_read_b128 v[242:245], v208 offset:36864
	ds_read_b128 v[246:249], v208 offset:38912
	global_load_lds_dwordx4 v[250:251], off
	v_lshl_add_u64 v[252:253], v[250:251], 0, s[20:21]
	s_mov_b32 m0, s81
	s_nop 0
	global_load_lds_dwordx4 v[252:253], off
	v_lshl_add_u64 v[252:253], v[250:251], 0, s[14:15]
	s_mov_b32 m0, s97
	v_lshl_add_u64 v[250:251], v[250:251], 0, s[22:23]
	global_load_lds_dwordx4 v[252:253], off
	s_mov_b32 m0, s64
	s_nop 0
	global_load_lds_dwordx4 v[250:251], off
	s_waitcnt vmcnt(8)
	s_waitcnt lgkmcnt(0)
	s_barrier
	v_mfma_f32_16x16x32_bf16 v[128:131], v[134:137], v[218:221], v[128:131]
	v_mfma_f32_16x16x32_bf16 v[128:131], v[138:141], v[226:229], v[128:131]
	v_mfma_f32_16x16x32_bf16 v[112:115], v[138:141], v[230:233], v[112:115]
	v_mfma_f32_16x16x32_bf16 v[112:115], v[134:137], v[222:225], v[112:115]
	v_mfma_f32_16x16x32_bf16 v[96:99], v[134:137], v[234:237], v[96:99]
	v_mfma_f32_16x16x32_bf16 v[96:99], v[138:141], v[242:245], v[96:99]
	v_mfma_f32_16x16x32_bf16 v[80:83], v[138:141], v[246:249], v[80:83]
	v_mfma_f32_16x16x32_bf16 v[80:83], v[134:137], v[238:241], v[80:83]
	v_mfma_f32_16x16x32_bf16 v[76:79], v[142:145], v[238:241], v[76:79]
	v_mfma_f32_16x16x32_bf16 v[76:79], v[146:149], v[246:249], v[76:79]
	v_mfma_f32_16x16x32_bf16 v[92:95], v[146:149], v[242:245], v[92:95]
	v_mfma_f32_16x16x32_bf16 v[92:95], v[142:145], v[234:237], v[92:95]
	v_mfma_f32_16x16x32_bf16 v[108:111], v[142:145], v[222:225], v[108:111]
	v_mfma_f32_16x16x32_bf16 v[108:111], v[146:149], v[230:233], v[108:111]
	v_mfma_f32_16x16x32_bf16 v[124:127], v[146:149], v[226:229], v[124:127]
	v_mfma_f32_16x16x32_bf16 v[124:127], v[142:145], v[218:221], v[124:127]
	v_mfma_f32_16x16x32_bf16 v[120:123], v[150:153], v[218:221], v[120:123]
	v_mfma_f32_16x16x32_bf16 v[120:123], v[174:177], v[226:229], v[120:123]
	v_mfma_f32_16x16x32_bf16 v[104:107], v[174:177], v[230:233], v[104:107]
	v_mfma_f32_16x16x32_bf16 v[104:107], v[150:153], v[222:225], v[104:107]
	v_mfma_f32_16x16x32_bf16 v[88:91], v[150:153], v[234:237], v[88:91]
	v_mfma_f32_16x16x32_bf16 v[88:91], v[174:177], v[242:245], v[88:91]
	v_mfma_f32_16x16x32_bf16 v[72:75], v[174:177], v[246:249], v[72:75]
	v_mfma_f32_16x16x32_bf16 v[72:75], v[150:153], v[238:241], v[72:75]
	v_mfma_f32_16x16x32_bf16 v[68:71], v[178:181], v[238:241], v[68:71]
	v_mfma_f32_16x16x32_bf16 v[68:71], v[182:185], v[246:249], v[68:71]
	v_mfma_f32_16x16x32_bf16 v[84:87], v[182:185], v[242:245], v[84:87]
	v_mfma_f32_16x16x32_bf16 v[84:87], v[178:181], v[234:237], v[84:87]
	v_mfma_f32_16x16x32_bf16 v[100:103], v[178:181], v[222:225], v[100:103]
	v_mfma_f32_16x16x32_bf16 v[100:103], v[182:185], v[230:233], v[100:103]
	v_mfma_f32_16x16x32_bf16 v[116:119], v[182:185], v[226:229], v[116:119]
	v_mfma_f32_16x16x32_bf16 v[116:119], v[178:181], v[218:221], v[116:119]
	s_barrier
	s_add_i32 s24, s70, s77
	v_lshl_add_u64 v[250:251], v[154:155], 0, s[48:49]
	s_mov_b32 m0, s24
	ds_read_b128 v[218:221], v207 offset:49152
	ds_read_b128 v[222:225], v207 offset:51200
	ds_read_b128 v[226:229], v208 offset:49152
	ds_read_b128 v[230:233], v208 offset:51200
	ds_read_b128 v[234:237], v207 offset:53248
	ds_read_b128 v[238:241], v207 offset:55296
	ds_read_b128 v[242:245], v208 offset:53248
	ds_read_b128 v[246:249], v208 offset:55296
	global_load_lds_dwordx4 v[250:251], off
	v_lshl_add_u64 v[250:251], v[154:155], 0, s[50:51]
	s_add_i32 m0, s24, 0x2000
	s_add_i32 s24, s71, s77
	global_load_lds_dwordx4 v[250:251], off
	v_lshl_add_u64 v[250:251], v[154:155], 0, s[52:53]
	s_mov_b32 m0, s24
	v_lshl_add_u64 v[154:155], v[154:155], 0, s[54:55]
	global_load_lds_dwordx4 v[250:251], off
	s_add_i32 m0, s24, 0x2000
	s_nop 0
	global_load_lds_dwordx4 v[154:155], off
	s_waitcnt vmcnt(4)
	s_waitcnt lgkmcnt(0)
	s_barrier
	v_mfma_f32_16x16x32_bf16 v[64:67], v[134:137], v[218:221], v[64:67]
	v_mfma_f32_16x16x32_bf16 v[64:67], v[138:141], v[226:229], v[64:67]
	v_mfma_f32_16x16x32_bf16 v[48:51], v[138:141], v[230:233], v[48:51]
	v_mfma_f32_16x16x32_bf16 v[48:51], v[134:137], v[222:225], v[48:51]
	v_mfma_f32_16x16x32_bf16 v[32:35], v[134:137], v[234:237], v[32:35]
	v_mfma_f32_16x16x32_bf16 v[32:35], v[138:141], v[242:245], v[32:35]
	v_mfma_f32_16x16x32_bf16 v[16:19], v[138:141], v[246:249], v[16:19]
	v_mfma_f32_16x16x32_bf16 v[16:19], v[134:137], v[238:241], v[16:19]
	v_mfma_f32_16x16x32_bf16 v[12:15], v[142:145], v[238:241], v[12:15]
	v_mfma_f32_16x16x32_bf16 v[12:15], v[146:149], v[246:249], v[12:15]
	v_mfma_f32_16x16x32_bf16 v[28:31], v[146:149], v[242:245], v[28:31]
	v_mfma_f32_16x16x32_bf16 v[28:31], v[142:145], v[234:237], v[28:31]
	v_mfma_f32_16x16x32_bf16 v[44:47], v[142:145], v[222:225], v[44:47]
	v_mfma_f32_16x16x32_bf16 v[44:47], v[146:149], v[230:233], v[44:47]
	v_mfma_f32_16x16x32_bf16 v[60:63], v[146:149], v[226:229], v[60:63]
	v_mfma_f32_16x16x32_bf16 v[60:63], v[142:145], v[218:221], v[60:63]
	v_mfma_f32_16x16x32_bf16 v[56:59], v[150:153], v[218:221], v[56:59]
	v_mfma_f32_16x16x32_bf16 v[56:59], v[174:177], v[226:229], v[56:59]
	v_mfma_f32_16x16x32_bf16 v[40:43], v[174:177], v[230:233], v[40:43]
	v_mfma_f32_16x16x32_bf16 v[40:43], v[150:153], v[222:225], v[40:43]
	v_mfma_f32_16x16x32_bf16 v[24:27], v[150:153], v[234:237], v[24:27]
	v_mfma_f32_16x16x32_bf16 v[24:27], v[174:177], v[242:245], v[24:27]
	v_mfma_f32_16x16x32_bf16 v[8:11], v[174:177], v[246:249], v[8:11]
	v_mfma_f32_16x16x32_bf16 v[8:11], v[150:153], v[238:241], v[8:11]
	v_mfma_f32_16x16x32_bf16 v[4:7], v[178:181], v[238:241], v[4:7]
	v_mfma_f32_16x16x32_bf16 v[4:7], v[182:185], v[246:249], v[4:7]
	v_mfma_f32_16x16x32_bf16 v[20:23], v[182:185], v[242:245], v[20:23]
	v_mfma_f32_16x16x32_bf16 v[20:23], v[178:181], v[234:237], v[20:23]
	v_mfma_f32_16x16x32_bf16 v[36:39], v[178:181], v[222:225], v[36:39]
	v_mfma_f32_16x16x32_bf16 v[36:39], v[182:185], v[230:233], v[36:39]
	v_mfma_f32_16x16x32_bf16 v[52:55], v[182:185], v[226:229], v[52:55]
	v_mfma_f32_16x16x32_bf16 v[52:55], v[178:181], v[218:221], v[52:55]
	s_barrier
	s_add_i32 s94, s94, 2
	s_add_u32 vcc_lo, vcc_lo, 0x100
	s_addc_u32 vcc_hi, vcc_hi, 0
	s_cmp_gt_u32 s94, 13
	s_cbranch_scc0 .LBB0_384
	s_and_b64 vcc, exec, s[56:57]
	s_cbranch_vccz .LBB0_387
	s_barrier
	s_setprio 2

.LBB0_1127:
	s_setprio 0
	s_andn2_b64 vcc, exec, s[10:11]
	s_mov_b32 s66, s58
	s_mov_b32 s64, s56
	s_mov_b64 s[68:69], s[62:63]
	s_mov_b64 s[26:27], s[60:61]
	s_cbranch_vccz .LBB0_1157

.LBB0_1135:
	ds_read_b128 v[168:171], v145
	ds_read_b128 v[174:177], v146
	ds_read_b128 v[178:181], v147
	ds_read_b128 v[182:185], v148
	ds_read_b128 v[194:197], v149
	ds_read_b128 v[198:201], v150
	ds_read_b128 v[202:205], v151
	ds_read_b128 v[206:209], v152
	s_add_u32 s70, s26, s68
	s_addc_u32 s71, s27, s69
	s_add_u32 s70, s70, 0x100
	s_addc_u32 s71, s71, 0
	s_add_u32 s84, s81, s68
	s_addc_u32 s85, s82, s69
	s_cmpk_eq_i32 s68, 0x700
	s_cselect_b32 s85, s59, s85
	s_cselect_b32 s84, s80, s84
	s_cselect_b32 s71, s57, s71
	s_cselect_b32 s70, s79, s70
	v_lshl_add_u64 v[140:141], v[138:139], 0, s[68:69]
	v_lshl_add_u64 v[242:243], v[140:141], 0, s[22:23]
	s_add_i32 m0, s34, 0x8000
	s_mov_b64 s[86:87], 0x20080
	ds_read_b128 v[210:213], v153
	ds_read_b128 v[214:217], v153 offset:2048
	ds_read_b128 v[218:221], v154
	ds_read_b128 v[222:225], v154 offset:2048
	ds_read_b128 v[226:229], v153 offset:4096
	ds_read_b128 v[230:233], v153 offset:6144
	ds_read_b128 v[234:237], v154 offset:4096
	ds_read_b128 v[238:241], v154 offset:6144
	global_load_lds_dwordx4 v[242:243], off
	v_lshl_add_u64 v[242:243], v[140:141], 0, s[86:87]
	s_add_i32 m0, s34, 0xa000
	s_mov_b64 s[86:87], 0x60080
	global_load_lds_dwordx4 v[242:243], off
	v_lshl_add_u64 v[242:243], v[140:141], 0, s[24:25]
	s_add_i32 m0, s34, 0xc000
	v_lshl_add_u64 v[140:141], v[140:141], 0, s[86:87]
	global_load_lds_dwordx4 v[242:243], off
	s_add_i32 m0, s34, 0xe000
	s_nop 0
	global_load_lds_dwordx4 v[140:141], off
	s_waitcnt vmcnt(8)
	s_waitcnt lgkmcnt(0)
	s_barrier
	v_mfma_f32_16x16x32_bf16 v[128:131], v[168:171], v[210:213], v[128:131]
	v_mfma_f32_16x16x32_bf16 v[128:131], v[174:177], v[218:221], v[128:131]
	v_mfma_f32_16x16x32_bf16 v[112:115], v[174:177], v[222:225], v[112:115]
	v_mfma_f32_16x16x32_bf16 v[112:115], v[168:171], v[214:217], v[112:115]
	v_mfma_f32_16x16x32_bf16 v[96:99], v[168:171], v[226:229], v[96:99]
	v_mfma_f32_16x16x32_bf16 v[96:99], v[174:177], v[234:237], v[96:99]
	v_mfma_f32_16x16x32_bf16 v[80:83], v[174:177], v[238:241], v[80:83]
	v_mfma_f32_16x16x32_bf16 v[80:83], v[168:171], v[230:233], v[80:83]
	v_mfma_f32_16x16x32_bf16 v[76:79], v[178:181], v[230:233], v[76:79]
	v_mfma_f32_16x16x32_bf16 v[76:79], v[182:185], v[238:241], v[76:79]
	v_mfma_f32_16x16x32_bf16 v[92:95], v[182:185], v[234:237], v[92:95]
	v_mfma_f32_16x16x32_bf16 v[92:95], v[178:181], v[226:229], v[92:95]
	v_mfma_f32_16x16x32_bf16 v[108:111], v[178:181], v[214:217], v[108:111]
	v_mfma_f32_16x16x32_bf16 v[108:111], v[182:185], v[222:225], v[108:111]
	v_mfma_f32_16x16x32_bf16 v[124:127], v[182:185], v[218:221], v[124:127]
	v_mfma_f32_16x16x32_bf16 v[124:127], v[178:181], v[210:213], v[124:127]
	v_mfma_f32_16x16x32_bf16 v[120:123], v[194:197], v[210:213], v[120:123]
	v_mfma_f32_16x16x32_bf16 v[120:123], v[198:201], v[218:221], v[120:123]
	v_mfma_f32_16x16x32_bf16 v[104:107], v[198:201], v[222:225], v[104:107]
	v_mfma_f32_16x16x32_bf16 v[104:107], v[194:197], v[214:217], v[104:107]
	v_mfma_f32_16x16x32_bf16 v[88:91], v[194:197], v[226:229], v[88:91]
	v_mfma_f32_16x16x32_bf16 v[88:91], v[198:201], v[234:237], v[88:91]
	v_mfma_f32_16x16x32_bf16 v[72:75], v[198:201], v[238:241], v[72:75]
	v_mfma_f32_16x16x32_bf16 v[72:75], v[194:197], v[230:233], v[72:75]
	v_mfma_f32_16x16x32_bf16 v[68:71], v[202:205], v[230:233], v[68:71]
	v_mfma_f32_16x16x32_bf16 v[68:71], v[206:209], v[238:241], v[68:71]
	v_mfma_f32_16x16x32_bf16 v[84:87], v[206:209], v[234:237], v[84:87]
	v_mfma_f32_16x16x32_bf16 v[84:87], v[202:205], v[226:229], v[84:87]
	v_mfma_f32_16x16x32_bf16 v[100:103], v[202:205], v[214:217], v[100:103]
	v_mfma_f32_16x16x32_bf16 v[100:103], v[206:209], v[222:225], v[100:103]
	v_mfma_f32_16x16x32_bf16 v[116:119], v[206:209], v[218:221], v[116:119]
	v_mfma_f32_16x16x32_bf16 v[116:119], v[202:205], v[210:213], v[116:119]
	s_barrier
	v_lshl_add_u64 v[140:141], s[84:85], 0, v[158:159]
	s_add_i32 s84, s67, s3
	s_mov_b32 m0, s84
	ds_read_b128 v[210:213], v153 offset:16384
	ds_read_b128 v[214:217], v153 offset:18432
	ds_read_b128 v[218:221], v154 offset:16384
	ds_read_b128 v[222:225], v154 offset:18432
	ds_read_b128 v[226:229], v153 offset:20480
	ds_read_b128 v[230:233], v153 offset:22528
	ds_read_b128 v[234:237], v154 offset:20480
	ds_read_b128 v[238:241], v154 offset:22528
	global_load_lds_dwordx4 v[140:141], off
	v_lshl_add_u64 v[242:243], v[140:141], 0, s[0:1]
	s_add_i32 m0, s84, 0x2000
	s_add_i32 s84, s72, s3
	global_load_lds_dwordx4 v[242:243], off
	v_lshl_add_u64 v[242:243], v[140:141], 0, s[12:13]
	s_mov_b32 m0, s84
	s_nop 0
	global_load_lds_dwordx4 v[242:243], off
	v_lshl_add_u64 v[242:243], v[140:141], 0, s[14:15]
	s_add_i32 m0, s84, 0x2000
	s_nop 0
	global_load_lds_dwordx4 v[242:243], off
	s_waitcnt vmcnt(4)
	s_waitcnt lgkmcnt(0)
	s_barrier
	v_mfma_f32_16x16x32_bf16 v[64:67], v[168:171], v[210:213], v[64:67]
	v_mfma_f32_16x16x32_bf16 v[64:67], v[174:177], v[218:221], v[64:67]
	v_mfma_f32_16x16x32_bf16 v[48:51], v[174:177], v[222:225], v[48:51]
	v_mfma_f32_16x16x32_bf16 v[48:51], v[168:171], v[214:217], v[48:51]
	v_mfma_f32_16x16x32_bf16 v[32:35], v[168:171], v[226:229], v[32:35]
	v_mfma_f32_16x16x32_bf16 v[32:35], v[174:177], v[234:237], v[32:35]
	v_mfma_f32_16x16x32_bf16 v[16:19], v[174:177], v[238:241], v[16:19]
	v_mfma_f32_16x16x32_bf16 v[16:19], v[168:171], v[230:233], v[16:19]
	v_mfma_f32_16x16x32_bf16 v[12:15], v[178:181], v[230:233], v[12:15]
	v_mfma_f32_16x16x32_bf16 v[12:15], v[182:185], v[238:241], v[12:15]
	v_mfma_f32_16x16x32_bf16 v[28:31], v[182:185], v[234:237], v[28:31]
	v_mfma_f32_16x16x32_bf16 v[28:31], v[178:181], v[226:229], v[28:31]
	v_mfma_f32_16x16x32_bf16 v[44:47], v[178:181], v[214:217], v[44:47]
	v_mfma_f32_16x16x32_bf16 v[44:47], v[182:185], v[222:225], v[44:47]
	v_mfma_f32_16x16x32_bf16 v[60:63], v[182:185], v[218:221], v[60:63]
	v_mfma_f32_16x16x32_bf16 v[60:63], v[178:181], v[210:213], v[60:63]
	v_mfma_f32_16x16x32_bf16 v[56:59], v[194:197], v[210:213], v[56:59]
	v_mfma_f32_16x16x32_bf16 v[56:59], v[198:201], v[218:221], v[56:59]
	v_mfma_f32_16x16x32_bf16 v[40:43], v[198:201], v[222:225], v[40:43]
	v_mfma_f32_16x16x32_bf16 v[40:43], v[194:197], v[214:217], v[40:43]
	v_mfma_f32_16x16x32_bf16 v[24:27], v[194:197], v[226:229], v[24:27]
	v_mfma_f32_16x16x32_bf16 v[24:27], v[198:201], v[234:237], v[24:27]
	v_mfma_f32_16x16x32_bf16 v[8:11], v[198:201], v[238:241], v[8:11]
	v_mfma_f32_16x16x32_bf16 v[8:11], v[194:197], v[230:233], v[8:11]
	v_mfma_f32_16x16x32_bf16 v[4:7], v[202:205], v[230:233], v[4:7]
	v_mfma_f32_16x16x32_bf16 v[4:7], v[206:209], v[238:241], v[4:7]
	v_mfma_f32_16x16x32_bf16 v[20:23], v[206:209], v[234:237], v[20:23]
	v_mfma_f32_16x16x32_bf16 v[20:23], v[202:205], v[226:229], v[20:23]
	v_mfma_f32_16x16x32_bf16 v[36:39], v[202:205], v[214:217], v[36:39]
	v_mfma_f32_16x16x32_bf16 v[36:39], v[206:209], v[222:225], v[36:39]
	v_mfma_f32_16x16x32_bf16 v[52:55], v[206:209], v[218:221], v[52:55]
	v_mfma_f32_16x16x32_bf16 v[52:55], v[202:205], v[210:213], v[52:55]
	s_barrier
	ds_read_b128 v[168:171], v163
	ds_read_b128 v[174:177], v164
	ds_read_b128 v[178:181], v155
	ds_read_b128 v[182:185], v160
	ds_read_b128 v[194:197], v165
	ds_read_b128 v[198:201], v166
	ds_read_b128 v[202:205], v161
	ds_read_b128 v[206:209], v162
	s_mov_b32 m0, s34
	v_lshl_add_u64 v[242:243], s[70:71], 0, v[0:1]
	ds_read_b128 v[210:213], v153 offset:32768
	ds_read_b128 v[214:217], v153 offset:34816
	ds_read_b128 v[218:221], v154 offset:32768
	ds_read_b128 v[222:225], v154 offset:34816
	ds_read_b128 v[226:229], v153 offset:36864
	ds_read_b128 v[230:233], v153 offset:38912
	ds_read_b128 v[234:237], v154 offset:36864
	ds_read_b128 v[238:241], v154 offset:38912
	global_load_lds_dwordx4 v[242:243], off
	v_lshl_add_u64 v[244:245], v[242:243], 0, s[16:17]
	s_mov_b32 m0, s35
	s_nop 0
	global_load_lds_dwordx4 v[244:245], off
	v_lshl_add_u64 v[244:245], v[242:243], 0, s[0:1]
	s_mov_b32 m0, s38
	v_lshl_add_u64 v[242:243], v[242:243], 0, s[18:19]
	global_load_lds_dwordx4 v[244:245], off
	s_mov_b32 m0, s39
	s_nop 0
	global_load_lds_dwordx4 v[242:243], off
	s_waitcnt vmcnt(8)
	s_waitcnt lgkmcnt(0)
	s_barrier
	v_mfma_f32_16x16x32_bf16 v[128:131], v[168:171], v[210:213], v[128:131]
	v_mfma_f32_16x16x32_bf16 v[128:131], v[174:177], v[218:221], v[128:131]
	v_mfma_f32_16x16x32_bf16 v[112:115], v[174:177], v[222:225], v[112:115]
	v_mfma_f32_16x16x32_bf16 v[112:115], v[168:171], v[214:217], v[112:115]
	v_mfma_f32_16x16x32_bf16 v[96:99], v[168:171], v[226:229], v[96:99]
	v_mfma_f32_16x16x32_bf16 v[96:99], v[174:177], v[234:237], v[96:99]
	v_mfma_f32_16x16x32_bf16 v[80:83], v[174:177], v[238:241], v[80:83]
	v_mfma_f32_16x16x32_bf16 v[80:83], v[168:171], v[230:233], v[80:83]
	v_mfma_f32_16x16x32_bf16 v[76:79], v[178:181], v[230:233], v[76:79]
	v_mfma_f32_16x16x32_bf16 v[76:79], v[182:185], v[238:241], v[76:79]
	v_mfma_f32_16x16x32_bf16 v[92:95], v[182:185], v[234:237], v[92:95]
	v_mfma_f32_16x16x32_bf16 v[92:95], v[178:181], v[226:229], v[92:95]
	v_mfma_f32_16x16x32_bf16 v[108:111], v[178:181], v[214:217], v[108:111]
	v_mfma_f32_16x16x32_bf16 v[108:111], v[182:185], v[222:225], v[108:111]
	v_mfma_f32_16x16x32_bf16 v[124:127], v[182:185], v[218:221], v[124:127]
	v_mfma_f32_16x16x32_bf16 v[124:127], v[178:181], v[210:213], v[124:127]
	v_mfma_f32_16x16x32_bf16 v[120:123], v[194:197], v[210:213], v[120:123]
	v_mfma_f32_16x16x32_bf16 v[120:123], v[198:201], v[218:221], v[120:123]
	v_mfma_f32_16x16x32_bf16 v[104:107], v[198:201], v[222:225], v[104:107]
	v_mfma_f32_16x16x32_bf16 v[104:107], v[194:197], v[214:217], v[104:107]
	v_mfma_f32_16x16x32_bf16 v[88:91], v[194:197], v[226:229], v[88:91]
	v_mfma_f32_16x16x32_bf16 v[88:91], v[198:201], v[234:237], v[88:91]
	v_mfma_f32_16x16x32_bf16 v[72:75], v[198:201], v[238:241], v[72:75]
	v_mfma_f32_16x16x32_bf16 v[72:75], v[194:197], v[230:233], v[72:75]
	v_mfma_f32_16x16x32_bf16 v[68:71], v[202:205], v[230:233], v[68:71]
	v_mfma_f32_16x16x32_bf16 v[68:71], v[206:209], v[238:241], v[68:71]
	v_mfma_f32_16x16x32_bf16 v[84:87], v[206:209], v[234:237], v[84:87]
	v_mfma_f32_16x16x32_bf16 v[84:87], v[202:205], v[226:229], v[84:87]
	v_mfma_f32_16x16x32_bf16 v[100:103], v[202:205], v[214:217], v[100:103]
	v_mfma_f32_16x16x32_bf16 v[100:103], v[206:209], v[222:225], v[100:103]
	v_mfma_f32_16x16x32_bf16 v[116:119], v[206:209], v[218:221], v[116:119]
	v_mfma_f32_16x16x32_bf16 v[116:119], v[202:205], v[210:213], v[116:119]
	s_barrier
	s_add_i32 s70, s73, s3
	v_lshl_add_u64 v[242:243], v[140:141], 0, s[22:23]
	s_mov_b32 m0, s70
	ds_read_b128 v[210:213], v153 offset:49152
	ds_read_b128 v[214:217], v153 offset:51200
	ds_read_b128 v[218:221], v154 offset:49152
	ds_read_b128 v[222:225], v154 offset:51200
	ds_read_b128 v[226:229], v153 offset:53248
	ds_read_b128 v[230:233], v153 offset:55296
	ds_read_b128 v[234:237], v154 offset:53248
	ds_read_b128 v[238:241], v154 offset:55296
	global_load_lds_dwordx4 v[242:243], off
	v_lshl_add_u64 v[242:243], v[140:141], 0, s[24:25]
	s_add_i32 m0, s70, 0x2000
	s_add_i32 s70, s77, s3
	global_load_lds_dwordx4 v[242:243], off
	v_lshl_add_u64 v[242:243], v[140:141], 0, s[28:29]
	s_mov_b32 m0, s70
	v_lshl_add_u64 v[140:141], v[140:141], 0, s[36:37]
	global_load_lds_dwordx4 v[242:243], off
	s_add_i32 m0, s70, 0x2000
	s_nop 0
	global_load_lds_dwordx4 v[140:141], off
	s_waitcnt vmcnt(4)
	s_waitcnt lgkmcnt(0)
	s_barrier
	v_mfma_f32_16x16x32_bf16 v[64:67], v[168:171], v[210:213], v[64:67]
	v_mfma_f32_16x16x32_bf16 v[64:67], v[174:177], v[218:221], v[64:67]
	v_mfma_f32_16x16x32_bf16 v[48:51], v[174:177], v[222:225], v[48:51]
	v_mfma_f32_16x16x32_bf16 v[48:51], v[168:171], v[214:217], v[48:51]
	v_mfma_f32_16x16x32_bf16 v[32:35], v[168:171], v[226:229], v[32:35]
	v_mfma_f32_16x16x32_bf16 v[32:35], v[174:177], v[234:237], v[32:35]
	v_mfma_f32_16x16x32_bf16 v[16:19], v[174:177], v[238:241], v[16:19]
	v_mfma_f32_16x16x32_bf16 v[16:19], v[168:171], v[230:233], v[16:19]
	v_mfma_f32_16x16x32_bf16 v[12:15], v[178:181], v[230:233], v[12:15]
	v_mfma_f32_16x16x32_bf16 v[12:15], v[182:185], v[238:241], v[12:15]
	v_mfma_f32_16x16x32_bf16 v[28:31], v[182:185], v[234:237], v[28:31]
	v_mfma_f32_16x16x32_bf16 v[28:31], v[178:181], v[226:229], v[28:31]
	v_mfma_f32_16x16x32_bf16 v[44:47], v[178:181], v[214:217], v[44:47]
	v_mfma_f32_16x16x32_bf16 v[44:47], v[182:185], v[222:225], v[44:47]
	v_mfma_f32_16x16x32_bf16 v[60:63], v[182:185], v[218:221], v[60:63]
	v_mfma_f32_16x16x32_bf16 v[60:63], v[178:181], v[210:213], v[60:63]
	v_mfma_f32_16x16x32_bf16 v[56:59], v[194:197], v[210:213], v[56:59]
	v_mfma_f32_16x16x32_bf16 v[56:59], v[198:201], v[218:221], v[56:59]
	v_mfma_f32_16x16x32_bf16 v[40:43], v[198:201], v[222:225], v[40:43]
	v_mfma_f32_16x16x32_bf16 v[40:43], v[194:197], v[214:217], v[40:43]
	v_mfma_f32_16x16x32_bf16 v[24:27], v[194:197], v[226:229], v[24:27]
	v_mfma_f32_16x16x32_bf16 v[24:27], v[198:201], v[234:237], v[24:27]
	v_mfma_f32_16x16x32_bf16 v[8:11], v[198:201], v[238:241], v[8:11]
	v_mfma_f32_16x16x32_bf16 v[8:11], v[194:197], v[230:233], v[8:11]
	v_mfma_f32_16x16x32_bf16 v[4:7], v[202:205], v[230:233], v[4:7]
	v_mfma_f32_16x16x32_bf16 v[4:7], v[206:209], v[238:241], v[4:7]
	v_mfma_f32_16x16x32_bf16 v[20:23], v[206:209], v[234:237], v[20:23]
	v_mfma_f32_16x16x32_bf16 v[20:23], v[202:205], v[226:229], v[20:23]
	v_mfma_f32_16x16x32_bf16 v[36:39], v[202:205], v[214:217], v[36:39]
	v_mfma_f32_16x16x32_bf16 v[36:39], v[206:209], v[222:225], v[36:39]
	v_mfma_f32_16x16x32_bf16 v[52:55], v[206:209], v[218:221], v[52:55]
	v_mfma_f32_16x16x32_bf16 v[52:55], v[202:205], v[210:213], v[52:55]
	s_barrier
	s_add_i32 s83, s83, 2
	s_add_u32 s68, s68, 0x100
	s_addc_u32 s69, s69, 0
	s_cmp_gt_u32 s83, 13
	s_cbranch_scc0 .LBB0_1135
	s_and_b64 vcc, exec, s[40:41]
	s_cbranch_vccz .LBB0_1138
	s_barrier
	s_setprio 2
